# mlstm_c tail: the four (norm-gain, out-gate) load pairs issued together before the unit's second barrier instead of one round at a time behind the previous store
# speedup vs baseline: 1.0041x; 1.0041x over previous
.Lmc_nowr:
	s_lshl_b32 s100, s31, 2
	s_add_u32 s100, s17, s100
	s_addc_u32 s101, s18, 0
	v_or_b32_e32 v60, v206, v240
	v_ashrrev_i32_e32 v61, 31, v60
	v_lshl_add_u64 v[62:63], v[60:61], 2, s[100:101]
	v_lshl_add_u64 v[80:81], v[216:217], 1, s[92:93]
	v_lshl_add_u64 v[80:81], v[80:81], 0, s[24:25]
	v_lshlrev_b64 v[82:83], 1, v[60:61]
	v_lshl_add_u64 v[80:81], v[80:81], 0, v[82:83]
	s_mov_b64 s[100:101], 0x19ca0800
	v_lshl_add_u64 v[80:81], v[80:81], 0, s[100:101]
	global_load_dwordx4 v[64:67], v[62:63], off
	global_load_dwordx2 v[84:85], v[80:81], off
	global_load_dwordx4 v[68:71], v[62:63], off offset:64
	global_load_dwordx2 v[86:87], v[80:81], off offset:32
	global_load_dwordx4 v[72:75], v[62:63], off offset:128
	global_load_dwordx2 v[88:89], v[80:81], off offset:64
	global_load_dwordx4 v[76:79], v[62:63], off offset:192
	global_load_dwordx2 v[90:91], v[80:81], off offset:96
	v_lshlrev_b32_e32 v0, 4, v220
	v_bitop3_b32 v0, v0, 64, v221 bitop3:0x36
	v_lshl_add_u32 v0, v0, 2, 0
	s_waitcnt lgkmcnt(0)
	s_barrier
	ds_read_b32 v0, v0 offset:768
	v_mov_b32_e32 v3, 0x22040
	ds_read_b32 v3, v3
	s_lshl_b32 s0, s31, 2
	s_add_u32 s0, s17, s0
	v_lshl_add_u64 v[16:17], v[216:217], 1, s[92:93]
	s_addc_u32 s1, s18, 0
	s_waitcnt lgkmcnt(0)
	v_add_f32_e32 v0, v2, v0
	v_fmamk_f32 v0, v0, 0x3c000000, v210
	v_cmp_gt_f32_e32 vcc, s67, v0
	v_mul_f32_e32 v2, 0x4b800000, v0
	v_lshl_add_u64 v[16:17], v[16:17], 0, s[24:25]
	v_cndmask_b32_e32 v0, v0, v2, vcc
	v_rsq_f32_e32 v0, v0
	v_lshlrev_b64 v[6:7], 12, v[218:219]
	v_readfirstlane_b32 s100, v3
	s_sub_i32 s101, s100, s30
	s_mov_b32 s30, s100
	v_mul_f32_e32 v2, 0x45800000, v0
	v_cndmask_b32_e32 v0, v0, v2, vcc
	v_or_b32_e32 v2, v206, v240
	v_ashrrev_i32_e32 v3, 31, v2
	v_lshlrev_b64 v[18:19], 1, v[2:3]
	v_lshl_add_u64 v[4:5], v[2:3], 2, s[0:1]
	v_lshl_add_u64 v[16:17], v[16:17], 0, v[18:19]
	s_mov_b64 s[0:1], 0x19ca0800
	v_lshl_add_u64 v[2:3], v[16:17], 0, s[0:1]
	v_add_co_u32_e32 v16, vcc, s56, v16
	s_nop 0
	v_addc_co_u32_e32 v17, vcc, 0, v17, vcc
	v_mul_f32_e32 v22, v58, v0
	v_readlane_b32 s0, v253, 60
	v_readlane_b32 s1, v253, 61
	v_mul_f32_e32 v8, v8, v0
	s_waitcnt vmcnt(6)
	v_mov_b32_e32 v12, v64
	v_mov_b32_e32 v13, v65
	v_mov_b32_e32 v14, v66
	v_mov_b32_e32 v15, v67
	v_mov_b32_e32 v16, v84
	v_mov_b32_e32 v17, v85
	v_mul_f32_e32 v12, v12, v22
	v_lshl_add_u64 v[6:7], s[0:1], 0, v[6:7]
	v_lshl_add_u64 v[6:7], v[6:7], 0, s[24:25]
	v_lshlrev_b32_e32 v20, 16, v16
	v_mul_f32_e32 v12, v12, v20
	v_mul_f32_e32 v20, v55, v0
	v_and_b32_e32 v16, 0xffff0000, v16
	v_mul_f32_e32 v13, v13, v20
	v_mul_f32_e32 v13, v13, v16
	v_mul_f32_e32 v16, v56, v0
	v_mul_f32_e32 v14, v14, v16
	v_mul_f32_e32 v16, v57, v0
	v_lshlrev_b32_e32 v21, 16, v17
	v_and_b32_e32 v17, 0xffff0000, v17
	v_mul_f32_e32 v15, v15, v16
	v_lshl_add_u64 v[6:7], v[6:7], 0, v[18:19]
	v_mul_f32_e32 v14, v14, v21
	v_mul_f32_e32 v15, v15, v17
	v_cvt_pk_bf16_f32 v12, v12, v13
	v_cvt_pk_bf16_f32 v13, v14, v15
	global_store_dwordx2 v[6:7], v[12:13], off
	s_nop 0
	v_mul_f32_e32 v20, v54, v0
	v_readlane_b32 s0, v254, 39
	s_lshl_b32 s19, s30, 4
	v_readlane_b32 s0, v254, 48
	v_readlane_b32 s1, v254, 49
	s_lshl_b32 s0, s101, 2
	s_add_u32 s2, s2, s0
	s_addc_u32 s3, s3, 0
	s_cmpk_gt_i32 s30, 0x1ff
	s_waitcnt vmcnt(5)
	v_mov_b32_e32 v12, v68
	v_mov_b32_e32 v13, v69
	v_mov_b32_e32 v14, v70
	v_mov_b32_e32 v15, v71
	v_mov_b32_e32 v16, v86
	v_mov_b32_e32 v17, v87
	v_mul_f32_e32 v12, v12, v20
	v_lshlrev_b32_e32 v18, 16, v16
	v_mul_f32_e32 v12, v12, v18
	v_mul_f32_e32 v18, v50, v0
	v_and_b32_e32 v16, 0xffff0000, v16
	v_mul_f32_e32 v13, v13, v18
	v_mul_f32_e32 v13, v13, v16
	v_mul_f32_e32 v16, v48, v0
	v_mul_f32_e32 v14, v14, v16
	v_mul_f32_e32 v16, v47, v0
	v_lshlrev_b32_e32 v19, 16, v17
	v_and_b32_e32 v17, 0xffff0000, v17
	v_mul_f32_e32 v15, v15, v16
	v_mul_f32_e32 v14, v14, v19
	v_mul_f32_e32 v15, v15, v17
	v_cvt_pk_bf16_f32 v12, v12, v13
	v_cvt_pk_bf16_f32 v13, v14, v15
	global_store_dwordx2 v[6:7], v[12:13], off offset:32
	s_nop 0
	v_mul_f32_e32 v20, v46, v0
	s_waitcnt vmcnt(4)
	v_mov_b32_e32 v12, v72
	v_mov_b32_e32 v13, v73
	v_mov_b32_e32 v14, v74
	v_mov_b32_e32 v15, v75
	v_mov_b32_e32 v16, v88
	v_mov_b32_e32 v17, v89
	v_mul_f32_e32 v12, v20, v12
	v_lshlrev_b32_e32 v18, 16, v16
	v_mul_f32_e32 v12, v12, v18
	v_mul_f32_e32 v18, v42, v0
	v_and_b32_e32 v16, 0xffff0000, v16
	v_mul_f32_e32 v13, v18, v13
	v_mul_f32_e32 v13, v13, v16
	v_mul_f32_e32 v16, v39, v0
	v_mul_f32_e32 v14, v16, v14
	v_mul_f32_e32 v16, v38, v0
	v_lshlrev_b32_e32 v19, 16, v17
	v_and_b32_e32 v17, 0xffff0000, v17
	v_mul_f32_e32 v15, v16, v15
	v_mul_f32_e32 v14, v14, v19
	v_mul_f32_e32 v15, v15, v17
	v_cvt_pk_bf16_f32 v12, v12, v13
	v_cvt_pk_bf16_f32 v13, v14, v15
	global_store_dwordx2 v[6:7], v[12:13], off offset:64
	s_nop 0
	s_waitcnt vmcnt(3)
	v_mov_b32_e32 v12, v76
	v_mov_b32_e32 v13, v77
	v_mov_b32_e32 v14, v78
	v_mov_b32_e32 v15, v79
	v_mov_b32_e32 v2, v90
	v_mov_b32_e32 v3, v91
	v_mul_f32_e32 v8, v8, v12
	v_lshlrev_b32_e32 v4, 16, v2
	v_mul_f32_e32 v4, v8, v4
	v_mul_f32_e32 v8, v9, v0
	v_and_b32_e32 v2, 0xffff0000, v2
	v_mul_f32_e32 v8, v8, v13
	v_mul_f32_e32 v2, v8, v2
	v_mul_f32_e32 v8, v10, v0
	v_mul_f32_e32 v0, v11, v0
	v_lshlrev_b32_e32 v5, 16, v3
	v_and_b32_e32 v3, 0xffff0000, v3
	v_mul_f32_e32 v8, v8, v14
	v_mul_f32_e32 v0, v0, v15
	v_mul_f32_e32 v5, v8, v5
	v_mul_f32_e32 v0, v0, v3
	v_cvt_pk_bf16_f32 v2, v4, v2
	v_cvt_pk_bf16_f32 v3, v5, v0
	global_store_dwordx2 v[6:7], v[2:3], off offset:96
	s_barrier
	s_cbranch_scc1 .LBB0_1362
